# 3-interval FFN-in K-loop v3: rows 0-31/64-95 of the second A half-tile (DMA'd by the leading half only) read in the load segment into spare VGPRs, the other rows read mid-segment with >= 36 MFMAs of l
# baseline (speedup 1.0000x reference)
; #define PG8_STAGE(bufoff, gbase, voff) do { _Pragma("unroll") for (int _i = 0; _i < 2; ++_i) \
;         __builtin_amdgcn_global_load_lds((const unsigned*)((const char*)(gbase) + (voff)[_i]), (PG8_LAS unsigned*)(lds + (bufoff) + ldsw + _i * 8192), 16, 0, 0); } while (0)
; #define PG8_LDA(dst, b, h) do { _Pragma("unroll") for (int m = 0; m < 4; ++m) _Pragma("unroll") for (int k = 0; k < 2; ++k) dst[m][k] = *(const PG8_LAS bf16x8*)(lds + PG8_SA(b, h) + aoff + m * 2048 + k * 1024); } while (0)
; #define PG8_LDB(dst, b, h) do { _Pragma("unroll") for (int n = 0; n < 2; ++n) _Pragma("unroll") for (int k = 0; k < 2; ++k) dst[n][k] = *(const PG8_LAS bf16x8*)(lds + PG8_SB(b, h) + boff + n * 2048 + k * 1024); } while (0)
; #define PG8_MMA(ai, bj, At, Bt) do { __builtin_amdgcn_s_setprio(1); _Pragma("unroll") for (int m = 0; m < 4; ++m) _Pragma("unroll") for (int n = 0; n < 2; ++n) _Pragma("unroll") for (int k = 0; k < 2; ++k) \
;         acc[ai][bj][m][n] = __builtin_amdgcn_mfma_f32_16x16x32_bf16(Bt[n][k], At[m][k], acc[ai][bj][m][n], 0, 0, 0); __builtin_amdgcn_s_setprio(0); } while (0)
; #define PG8_WAIT_V(n) asm volatile("s_waitcnt vmcnt(" #n ")" ::: "memory")
; #define PG8_WAIT_L(n) asm volatile("s_waitcnt lgkmcnt(" #n ")" ::: "memory")
; #define PG8_BAR __builtin_amdgcn_s_barrier()
; template <class Epi, class Sched, bool ALIGN_EPI = false, bool SP2 = false>
; __device__ __forceinline__ void gemm_phase(PG8_LAS unsigned char* lds, const Gemm g, const Sched& S, const Epi& E) {
;     ...
;             const char* a1 = cA + (size_t)(t + 1) * kstep;
;             const char* a2 = last ? nA : cA + (size_t)(t + 2) * kstep; const char* b2 = last ? nB : cB + (size_t)(t + 2) * kstep;
;             const char* a3 = a2 + kstep; const char* b3 = b2 + kstep;
;             if (last && has_next) S.a_ready(nxt);
;             if constexpr (SP2) {
;             PG8_LDB(B0, 0, 0); PG8_LDB(B1, 0, 1); PG8_SCHED; PG8_LDA(At, 0, 0); PG8_STAGE(PG8_SA(1, 1), a1 + hstep, voffA);
;             PG8_WAIT_V(8); PG8_WAIT_L(0); PG8_BAR; PG8_MMA(0, 0, At, B0); PG8_MMA(0, 1, At, B1); PG8_BAR; PG8_SCHED;
;             PG8_LDA(At, 0, 1); PG8_STAGE(PG8_SB(0, 0), b2, voffB); PG8_STAGE(PG8_SB(0, 1), b2 + hstep, voffB); PG8_STAGE(PG8_SA(0, 0), a2, voffA);
;             PG8_WAIT_V(8); PG8_WAIT_L(0); PG8_BAR; PG8_MMA(1, 0, At, B0); PG8_MMA(1, 1, At, B1); PG8_BAR; PG8_SCHED;
.Lffn_kA:
	s_add_u32 s46, s44, 0xfffc0080
	s_addc_u32 s47, s45, -1
	s_add_u32 s70, s44, 0x100
	s_addc_u32 s71, s45, 0
	s_add_u32 s72, s62, 0x40080
	s_addc_u32 s73, s17, 0
	s_cmp_eq_u32 s66, 12
	s_cselect_b32 s49, s17, s47
	s_cselect_b32 s48, s62, s46
	s_cselect_b32 s47, s15, s65
	s_cselect_b32 s46, s63, s64
	s_cselect_b32 s70, s72, s70
	s_cselect_b32 s71, s73, s71
	s_add_u32 s68, s46, 0x40000
	s_addc_u32 s69, s47, 0
	s_add_u32 s100, s48, 0x40000
	s_addc_u32 s101, s49, 0
	s_add_i32 m0, s39, 0xc000
	s_nop 0
	global_load_lds_dwordx4 v138, s[44:45]
	s_add_i32 m0, s39, 0xe000
	s_nop 0
	global_load_lds_dwordx4 v140, s[44:45]
	v_add_u32_e32 v145, 0x10000, v143
	ds_read_b128 v[146:149], v145
	ds_read_b128 v[150:153], v145 offset:1024
	ds_read_b128 v[154:157], v145 offset:2048
	ds_read_b128 v[158:161], v145 offset:3072
	v_add_u32_e32 v145, 0x14000, v143
	ds_read_b128 v[176:179], v145
	ds_read_b128 v[180:183], v145 offset:1024
	ds_read_b128 v[184:187], v145 offset:2048
	ds_read_b128 v[188:191], v145 offset:3072
	ds_read_b128 v[192:195], v144
	ds_read_b128 v[196:199], v144 offset:1024
	ds_read_b128 v[208:211], v144 offset:2048
	ds_read_b128 v[212:215], v144 offset:3072
	ds_read_b128 v[216:219], v144 offset:4096
	ds_read_b128 v[220:223], v144 offset:5120
	ds_read_b128 v[224:227], v144 offset:6144
	ds_read_b128 v[228:231], v144 offset:7168
	ds_read_b128 v[232:235], v144 offset:16384
	ds_read_b128 v[236:239], v144 offset:17408
	ds_read_b128 v[240:243], v144 offset:18432
	ds_read_b128 v[244:247], v144 offset:19456
	s_waitcnt lgkmcnt(0)
	s_setprio 1
	s_barrier
	v_mfma_f32_16x16x32_bf16 v[126:129], v[146:149], v[192:195], v[126:129]
	v_mfma_f32_16x16x32_bf16 v[118:121], v[154:157], v[192:195], v[118:121]
	v_mfma_f32_16x16x32_bf16 v[122:125], v[176:179], v[192:195], v[122:125]
	v_mfma_f32_16x16x32_bf16 v[114:117], v[184:187], v[192:195], v[114:117]
	v_mfma_f32_16x16x32_bf16 v[126:129], v[150:153], v[196:199], v[126:129]
	v_mfma_f32_16x16x32_bf16 v[118:121], v[158:161], v[196:199], v[118:121]
	v_mfma_f32_16x16x32_bf16 v[122:125], v[180:183], v[196:199], v[122:125]
	v_mfma_f32_16x16x32_bf16 v[114:117], v[188:191], v[196:199], v[114:117]
	ds_read_b128 v[192:195], v144 offset:20480
	ds_read_b128 v[196:199], v144 offset:21504
	v_mfma_f32_16x16x32_bf16 v[110:113], v[146:149], v[208:211], v[110:113]
	v_mfma_f32_16x16x32_bf16 v[102:105], v[154:157], v[208:211], v[102:105]
	v_mfma_f32_16x16x32_bf16 v[106:109], v[176:179], v[208:211], v[106:109]
	v_mfma_f32_16x16x32_bf16 v[98:101], v[184:187], v[208:211], v[98:101]
	v_mfma_f32_16x16x32_bf16 v[110:113], v[150:153], v[212:215], v[110:113]
	v_mfma_f32_16x16x32_bf16 v[102:105], v[158:161], v[212:215], v[102:105]
	v_mfma_f32_16x16x32_bf16 v[106:109], v[180:183], v[212:215], v[106:109]
	v_mfma_f32_16x16x32_bf16 v[98:101], v[188:191], v[212:215], v[98:101]
	ds_read_b128 v[208:211], v144 offset:22528
	ds_read_b128 v[212:215], v144 offset:23552
	v_mfma_f32_16x16x32_bf16 v[94:97], v[146:149], v[216:219], v[94:97]
	v_mfma_f32_16x16x32_bf16 v[86:89], v[154:157], v[216:219], v[86:89]
	v_mfma_f32_16x16x32_bf16 v[90:93], v[176:179], v[216:219], v[90:93]
	v_mfma_f32_16x16x32_bf16 v[82:85], v[184:187], v[216:219], v[82:85]
	v_mfma_f32_16x16x32_bf16 v[94:97], v[150:153], v[220:223], v[94:97]
	v_mfma_f32_16x16x32_bf16 v[86:89], v[158:161], v[220:223], v[86:89]
	v_mfma_f32_16x16x32_bf16 v[90:93], v[180:183], v[220:223], v[90:93]
	v_mfma_f32_16x16x32_bf16 v[82:85], v[188:191], v[220:223], v[82:85]
	v_mfma_f32_16x16x32_bf16 v[76:79], v[146:149], v[224:227], v[76:79]
	v_mfma_f32_16x16x32_bf16 v[68:71], v[154:157], v[224:227], v[68:71]
	v_mfma_f32_16x16x32_bf16 v[72:75], v[176:179], v[224:227], v[72:75]
	v_mfma_f32_16x16x32_bf16 v[64:67], v[184:187], v[224:227], v[64:67]
	v_mfma_f32_16x16x32_bf16 v[76:79], v[150:153], v[228:231], v[76:79]
	v_mfma_f32_16x16x32_bf16 v[68:71], v[158:161], v[228:231], v[68:71]
	v_mfma_f32_16x16x32_bf16 v[72:75], v[180:183], v[228:231], v[72:75]
	v_mfma_f32_16x16x32_bf16 v[64:67], v[188:191], v[228:231], v[64:67]
	v_mfma_f32_16x16x32_bf16 v[60:63], v[146:149], v[232:235], v[60:63]
	v_mfma_f32_16x16x32_bf16 v[52:55], v[154:157], v[232:235], v[52:55]
	v_mfma_f32_16x16x32_bf16 v[56:59], v[176:179], v[232:235], v[56:59]
	v_mfma_f32_16x16x32_bf16 v[48:51], v[184:187], v[232:235], v[48:51]
	v_mfma_f32_16x16x32_bf16 v[60:63], v[150:153], v[236:239], v[60:63]
	v_mfma_f32_16x16x32_bf16 v[52:55], v[158:161], v[236:239], v[52:55]
	v_mfma_f32_16x16x32_bf16 v[56:59], v[180:183], v[236:239], v[56:59]
	v_mfma_f32_16x16x32_bf16 v[48:51], v[188:191], v[236:239], v[48:51]
	v_mfma_f32_16x16x32_bf16 v[44:47], v[146:149], v[240:243], v[44:47]
	v_mfma_f32_16x16x32_bf16 v[36:39], v[154:157], v[240:243], v[36:39]
	v_mfma_f32_16x16x32_bf16 v[40:43], v[176:179], v[240:243], v[40:43]
	v_mfma_f32_16x16x32_bf16 v[32:35], v[184:187], v[240:243], v[32:35]
	v_mfma_f32_16x16x32_bf16 v[44:47], v[150:153], v[244:247], v[44:47]
	v_mfma_f32_16x16x32_bf16 v[36:39], v[158:161], v[244:247], v[36:39]
	v_mfma_f32_16x16x32_bf16 v[40:43], v[180:183], v[244:247], v[40:43]
	v_mfma_f32_16x16x32_bf16 v[32:35], v[188:191], v[244:247], v[32:35]
	s_waitcnt lgkmcnt(2)
	v_mfma_f32_16x16x32_bf16 v[28:31], v[146:149], v[192:195], v[28:31]
	v_mfma_f32_16x16x32_bf16 v[20:23], v[154:157], v[192:195], v[20:23]
	v_mfma_f32_16x16x32_bf16 v[24:27], v[176:179], v[192:195], v[24:27]
	v_mfma_f32_16x16x32_bf16 v[16:19], v[184:187], v[192:195], v[16:19]
	v_mfma_f32_16x16x32_bf16 v[28:31], v[150:153], v[196:199], v[28:31]
	v_mfma_f32_16x16x32_bf16 v[20:23], v[158:161], v[196:199], v[20:23]
	v_mfma_f32_16x16x32_bf16 v[24:27], v[180:183], v[196:199], v[24:27]
	v_mfma_f32_16x16x32_bf16 v[16:19], v[188:191], v[196:199], v[16:19]
	s_waitcnt lgkmcnt(0)
	v_mfma_f32_16x16x32_bf16 v[12:15], v[146:149], v[208:211], v[12:15]
	v_mfma_f32_16x16x32_bf16 v[4:7], v[154:157], v[208:211], v[4:7]
	v_mfma_f32_16x16x32_bf16 v[8:11], v[176:179], v[208:211], v[8:11]
	v_mfma_f32_16x16x32_bf16 v[0:3], v[184:187], v[208:211], v[0:3]
	v_mfma_f32_16x16x32_bf16 v[12:15], v[150:153], v[212:215], v[12:15]
	v_mfma_f32_16x16x32_bf16 v[4:7], v[158:161], v[212:215], v[4:7]
	v_mfma_f32_16x16x32_bf16 v[8:11], v[180:183], v[212:215], v[8:11]
	v_mfma_f32_16x16x32_bf16 v[0:3], v[188:191], v[212:215], v[0:3]
	s_waitcnt vmcnt(2)
	s_setprio 0
	s_barrier
; #define PG8_STAGE(bufoff, gbase, voff) do { _Pragma("unroll") for (int _i = 0; _i < 2; ++_i) \
;         __builtin_amdgcn_global_load_lds((const unsigned*)((const char*)(gbase) + (voff)[_i]), (PG8_LAS unsigned*)(lds + (bufoff) + ldsw + _i * 8192), 16, 0, 0); } while (0)
; #define PG8_LDA(dst, b, h) do { _Pragma("unroll") for (int m = 0; m < 4; ++m) _Pragma("unroll") for (int k = 0; k < 2; ++k) dst[m][k] = *(const PG8_LAS bf16x8*)(lds + PG8_SA(b, h) + aoff + m * 2048 + k * 1024); } while (0)
; #define PG8_LDB(dst, b, h) do { _Pragma("unroll") for (int n = 0; n < 2; ++n) _Pragma("unroll") for (int k = 0; k < 2; ++k) dst[n][k] = *(const PG8_LAS bf16x8*)(lds + PG8_SB(b, h) + boff + n * 2048 + k * 1024); } while (0)
; #define PG8_MMA(ai, bj, At, Bt) do { __builtin_amdgcn_s_setprio(1); _Pragma("unroll") for (int m = 0; m < 4; ++m) _Pragma("unroll") for (int n = 0; n < 2; ++n) _Pragma("unroll") for (int k = 0; k < 2; ++k) \
;         acc[ai][bj][m][n] = __builtin_amdgcn_mfma_f32_16x16x32_bf16(Bt[n][k], At[m][k], acc[ai][bj][m][n], 0, 0, 0); __builtin_amdgcn_s_setprio(0); } while (0)
; #define PG8_WAIT_V(n) asm volatile("s_waitcnt vmcnt(" #n ")" ::: "memory")
; #define PG8_WAIT_L(n) asm volatile("s_waitcnt lgkmcnt(" #n ")" ::: "memory")
; #define PG8_BAR __builtin_amdgcn_s_barrier()
; #define PG8_SCHED __builtin_amdgcn_sched_barrier(0)
; template <class Epi, class Sched, bool ALIGN_EPI = false, bool SP2 = false>
; __device__ __forceinline__ void gemm_phase(PG8_LAS unsigned char* lds, const Gemm g, const Sched& S, const Epi& E) {
;     ...
;             PG8_LDA(At, 0, 1); PG8_STAGE(PG8_SB(0, 0), b2, voffB); PG8_STAGE(PG8_SB(0, 1), b2 + hstep, voffB); PG8_STAGE(PG8_SA(0, 0), a2, voffA);
;             PG8_WAIT_V(8); PG8_WAIT_L(0); PG8_BAR; PG8_MMA(1, 0, At, B0); PG8_MMA(1, 1, At, B1); PG8_BAR; PG8_SCHED;
;             PG8_LDB(B0, 1, 0); PG8_LDB(B1, 1, 1); PG8_SCHED; PG8_LDA(At, 1, 0); PG8_STAGE(PG8_SA(0, 1), a2 + hstep, voffA);
;             PG8_WAIT_V(8); PG8_WAIT_L(0); PG8_BAR; PG8_MMA(0, 0, At, B0); PG8_MMA(0, 1, At, B1); PG8_BAR; PG8_SCHED;
	s_add_i32 m0, s39, 0x10000
	s_nop 0
	global_load_lds_dwordx4 v134, s[46:47]
	s_add_i32 m0, s39, 0x12000
	s_nop 0
	global_load_lds_dwordx4 v130, s[46:47]
	s_add_i32 m0, s39, 0x14000
	s_nop 0
	global_load_lds_dwordx4 v134, s[68:69]
	s_add_i32 m0, s39, 0x16000
	s_nop 0
	global_load_lds_dwordx4 v130, s[68:69]
	s_add_i32 m0, s39, 0x0
	s_nop 0
	global_load_lds_dwordx4 v136, s[48:49]
	s_add_i32 m0, s39, 0x2000
	s_nop 0
	global_load_lds_dwordx4 v132, s[48:49]
	s_add_i32 m0, s39, 0x4000
	s_nop 0
	global_load_lds_dwordx4 v136, s[100:101]
	s_add_i32 m0, s39, 0x6000
	s_nop 0
	global_load_lds_dwordx4 v132, s[100:101]
	v_add_u32_e32 v145, 0x18000, v143
	ds_read_b128 v[146:149], v145
	ds_read_b128 v[150:153], v145 offset:1024
	ds_read_b128 v[154:157], v145 offset:2048
	ds_read_b128 v[158:161], v145 offset:3072
	v_add_u32_e32 v145, 0x1c000, v143
	ds_read_b128 v[176:179], v145
	ds_read_b128 v[180:183], v145 offset:1024
	ds_read_b128 v[184:187], v145 offset:2048
	ds_read_b128 v[188:191], v145 offset:3072
	ds_read_b128 v[192:195], v144 offset:32768
	ds_read_b128 v[196:199], v144 offset:33792
	ds_read_b128 v[208:211], v144 offset:34816
	ds_read_b128 v[212:215], v144 offset:35840
	ds_read_b128 v[216:219], v144 offset:36864
	ds_read_b128 v[220:223], v144 offset:37888
	ds_read_b128 v[224:227], v144 offset:38912
	ds_read_b128 v[228:231], v144 offset:39936
	s_waitcnt lgkmcnt(0)
	s_setprio 1
	s_barrier
	v_mfma_f32_16x16x32_bf16 v[126:129], v[146:149], v[192:195], v[126:129]
	v_mfma_f32_16x16x32_bf16 v[118:121], v[154:157], v[192:195], v[118:121]
	v_mfma_f32_16x16x32_bf16 v[122:125], v[176:179], v[192:195], v[122:125]
	v_mfma_f32_16x16x32_bf16 v[114:117], v[184:187], v[192:195], v[114:117]
	v_mfma_f32_16x16x32_bf16 v[126:129], v[150:153], v[196:199], v[126:129]
	v_mfma_f32_16x16x32_bf16 v[118:121], v[158:161], v[196:199], v[118:121]
	v_mfma_f32_16x16x32_bf16 v[122:125], v[180:183], v[196:199], v[122:125]
	v_mfma_f32_16x16x32_bf16 v[114:117], v[188:191], v[196:199], v[114:117]
	v_mfma_f32_16x16x32_bf16 v[110:113], v[146:149], v[208:211], v[110:113]
	v_mfma_f32_16x16x32_bf16 v[102:105], v[154:157], v[208:211], v[102:105]
	v_mfma_f32_16x16x32_bf16 v[106:109], v[176:179], v[208:211], v[106:109]
	v_mfma_f32_16x16x32_bf16 v[98:101], v[184:187], v[208:211], v[98:101]
	v_mfma_f32_16x16x32_bf16 v[110:113], v[150:153], v[212:215], v[110:113]
	v_mfma_f32_16x16x32_bf16 v[102:105], v[158:161], v[212:215], v[102:105]
	v_mfma_f32_16x16x32_bf16 v[106:109], v[180:183], v[212:215], v[106:109]
	v_mfma_f32_16x16x32_bf16 v[98:101], v[188:191], v[212:215], v[98:101]
	v_mfma_f32_16x16x32_bf16 v[94:97], v[146:149], v[216:219], v[94:97]
	v_mfma_f32_16x16x32_bf16 v[86:89], v[154:157], v[216:219], v[86:89]
	v_mfma_f32_16x16x32_bf16 v[90:93], v[176:179], v[216:219], v[90:93]
	v_mfma_f32_16x16x32_bf16 v[82:85], v[184:187], v[216:219], v[82:85]
	v_mfma_f32_16x16x32_bf16 v[94:97], v[150:153], v[220:223], v[94:97]
	v_mfma_f32_16x16x32_bf16 v[86:89], v[158:161], v[220:223], v[86:89]
	v_mfma_f32_16x16x32_bf16 v[90:93], v[180:183], v[220:223], v[90:93]
	v_mfma_f32_16x16x32_bf16 v[82:85], v[188:191], v[220:223], v[82:85]
	v_mfma_f32_16x16x32_bf16 v[76:79], v[146:149], v[224:227], v[76:79]
	v_mfma_f32_16x16x32_bf16 v[68:71], v[154:157], v[224:227], v[68:71]
	v_mfma_f32_16x16x32_bf16 v[72:75], v[176:179], v[224:227], v[72:75]
	v_mfma_f32_16x16x32_bf16 v[64:67], v[184:187], v[224:227], v[64:67]
	v_mfma_f32_16x16x32_bf16 v[76:79], v[150:153], v[228:231], v[76:79]
	v_mfma_f32_16x16x32_bf16 v[68:71], v[158:161], v[228:231], v[68:71]
	v_mfma_f32_16x16x32_bf16 v[72:75], v[180:183], v[228:231], v[72:75]
	v_mfma_f32_16x16x32_bf16 v[64:67], v[188:191], v[228:231], v[64:67]
	s_waitcnt vmcnt(8)
	s_setprio 0
	s_barrier
	s_add_u32 s46, s46, 0x80
	s_addc_u32 s47, s47, 0
	s_add_u32 s68, s68, 0x80
	s_addc_u32 s69, s69, 0
	s_add_u32 s48, s48, 0x80
	s_addc_u32 s49, s49, 0
	s_add_i32 m0, s39, 0x18000
	s_nop 0
	global_load_lds_dwordx4 v134, s[46:47]
	s_add_i32 m0, s39, 0x1a000
	s_nop 0
	global_load_lds_dwordx4 v130, s[46:47]
	s_add_i32 m0, s39, 0x1c000
	s_nop 0
	global_load_lds_dwordx4 v134, s[68:69]
	s_add_i32 m0, s39, 0x1e000
	s_nop 0
	global_load_lds_dwordx4 v130, s[68:69]
	s_add_i32 m0, s39, 0x8000
	s_nop 0
	global_load_lds_dwordx4 v136, s[48:49]
	s_add_i32 m0, s39, 0xa000
	s_nop 0
	global_load_lds_dwordx4 v132, s[48:49]
	ds_read_b128 v[192:195], v144 offset:49152
	ds_read_b128 v[196:199], v144 offset:50176
	ds_read_b128 v[208:211], v144 offset:51200
	ds_read_b128 v[212:215], v144 offset:52224
	ds_read_b128 v[216:219], v144 offset:53248
	ds_read_b128 v[220:223], v144 offset:54272
	ds_read_b128 v[224:227], v144 offset:55296
	ds_read_b128 v[228:231], v144 offset:56320
	s_waitcnt lgkmcnt(0)
	s_setprio 1
	s_barrier
; #define PG8_STAGE(bufoff, gbase, voff) do { _Pragma("unroll") for (int _i = 0; _i < 2; ++_i) \
;         __builtin_amdgcn_global_load_lds((const unsigned*)((const char*)(gbase) + (voff)[_i]), (PG8_LAS unsigned*)(lds + (bufoff) + ldsw + _i * 8192), 16, 0, 0); } while (0)
; #define PG8_LDA(dst, b, h) do { _Pragma("unroll") for (int m = 0; m < 4; ++m) _Pragma("unroll") for (int k = 0; k < 2; ++k) dst[m][k] = *(const PG8_LAS bf16x8*)(lds + PG8_SA(b, h) + aoff + m * 2048 + k * 1024); } while (0)
; #define PG8_LDB(dst, b, h) do { _Pragma("unroll") for (int n = 0; n < 2; ++n) _Pragma("unroll") for (int k = 0; k < 2; ++k) dst[n][k] = *(const PG8_LAS bf16x8*)(lds + PG8_SB(b, h) + boff + n * 2048 + k * 1024); } while (0)
; #define PG8_MMA(ai, bj, At, Bt) do { __builtin_amdgcn_s_setprio(1); _Pragma("unroll") for (int m = 0; m < 4; ++m) _Pragma("unroll") for (int n = 0; n < 2; ++n) _Pragma("unroll") for (int k = 0; k < 2; ++k) \
;         acc[ai][bj][m][n] = __builtin_amdgcn_mfma_f32_16x16x32_bf16(Bt[n][k], At[m][k], acc[ai][bj][m][n], 0, 0, 0); __builtin_amdgcn_s_setprio(0); } while (0)
; #define PG8_WAIT_V(n) asm volatile("s_waitcnt vmcnt(" #n ")" ::: "memory")
; #define PG8_WAIT_L(n) asm volatile("s_waitcnt lgkmcnt(" #n ")" ::: "memory")
; #define PG8_BAR __builtin_amdgcn_s_barrier()
; template <class Epi, class Sched, bool ALIGN_EPI = false, bool SP2 = false>
; __device__ __forceinline__ void gemm_phase(PG8_LAS unsigned char* lds, const Gemm g, const Sched& S, const Epi& E) {
;     ...
;             const char* a1 = cA + (size_t)(t + 1) * kstep;
;             const char* a2 = last ? nA : cA + (size_t)(t + 2) * kstep; const char* b2 = last ? nB : cB + (size_t)(t + 2) * kstep;
;             const char* a3 = a2 + kstep; const char* b3 = b2 + kstep;
;             if (last && has_next) S.a_ready(nxt);
;             if constexpr (SP2) {
;             PG8_LDB(B0, 0, 0); PG8_LDB(B1, 0, 1); PG8_SCHED; PG8_LDA(At, 0, 0); PG8_STAGE(PG8_SA(1, 1), a1 + hstep, voffA);
;             PG8_WAIT_V(8); PG8_WAIT_L(0); PG8_BAR; PG8_MMA(0, 0, At, B0); PG8_MMA(0, 1, At, B1); PG8_BAR; PG8_SCHED;
;     ...
;             PG8_LDA(At, 1, 1); PG8_STAGE(PG8_SB(1, 0), b3, voffB); PG8_STAGE(PG8_SB(1, 1), b3 + hstep, voffB); PG8_STAGE(PG8_SA(1, 0), a3, voffA);
;             PG8_WAIT_V(8); PG8_WAIT_L(0); PG8_BAR; PG8_MMA(1, 0, At, B0); PG8_MMA(1, 1, At, B1); PG8_BAR; PG8_SCHED;
	v_mfma_f32_16x16x32_bf16 v[60:63], v[146:149], v[192:195], v[60:63]
	v_mfma_f32_16x16x32_bf16 v[52:55], v[154:157], v[192:195], v[52:55]
	v_mfma_f32_16x16x32_bf16 v[56:59], v[176:179], v[192:195], v[56:59]
	v_mfma_f32_16x16x32_bf16 v[48:51], v[184:187], v[192:195], v[48:51]
	v_mfma_f32_16x16x32_bf16 v[60:63], v[150:153], v[196:199], v[60:63]
	v_mfma_f32_16x16x32_bf16 v[52:55], v[158:161], v[196:199], v[52:55]
	v_mfma_f32_16x16x32_bf16 v[56:59], v[180:183], v[196:199], v[56:59]
	v_mfma_f32_16x16x32_bf16 v[48:51], v[188:191], v[196:199], v[48:51]
	v_mfma_f32_16x16x32_bf16 v[44:47], v[146:149], v[208:211], v[44:47]
	v_mfma_f32_16x16x32_bf16 v[36:39], v[154:157], v[208:211], v[36:39]
	v_mfma_f32_16x16x32_bf16 v[40:43], v[176:179], v[208:211], v[40:43]
	v_mfma_f32_16x16x32_bf16 v[32:35], v[184:187], v[208:211], v[32:35]
	v_mfma_f32_16x16x32_bf16 v[44:47], v[150:153], v[212:215], v[44:47]
	v_mfma_f32_16x16x32_bf16 v[36:39], v[158:161], v[212:215], v[36:39]
	v_mfma_f32_16x16x32_bf16 v[40:43], v[180:183], v[212:215], v[40:43]
	v_mfma_f32_16x16x32_bf16 v[32:35], v[188:191], v[212:215], v[32:35]
	v_mfma_f32_16x16x32_bf16 v[28:31], v[146:149], v[216:219], v[28:31]
	v_mfma_f32_16x16x32_bf16 v[20:23], v[154:157], v[216:219], v[20:23]
	v_mfma_f32_16x16x32_bf16 v[24:27], v[176:179], v[216:219], v[24:27]
	v_mfma_f32_16x16x32_bf16 v[16:19], v[184:187], v[216:219], v[16:19]
	v_mfma_f32_16x16x32_bf16 v[28:31], v[150:153], v[220:223], v[28:31]
	v_mfma_f32_16x16x32_bf16 v[20:23], v[158:161], v[220:223], v[20:23]
	v_mfma_f32_16x16x32_bf16 v[24:27], v[180:183], v[220:223], v[24:27]
	v_mfma_f32_16x16x32_bf16 v[16:19], v[188:191], v[220:223], v[16:19]
	v_mfma_f32_16x16x32_bf16 v[12:15], v[146:149], v[224:227], v[12:15]
	v_mfma_f32_16x16x32_bf16 v[4:7], v[154:157], v[224:227], v[4:7]
	v_mfma_f32_16x16x32_bf16 v[8:11], v[176:179], v[224:227], v[8:11]
	v_mfma_f32_16x16x32_bf16 v[0:3], v[184:187], v[224:227], v[0:3]
	v_mfma_f32_16x16x32_bf16 v[12:15], v[150:153], v[228:231], v[12:15]
	v_mfma_f32_16x16x32_bf16 v[4:7], v[158:161], v[228:231], v[4:7]
	v_mfma_f32_16x16x32_bf16 v[8:11], v[180:183], v[228:231], v[8:11]
	v_mfma_f32_16x16x32_bf16 v[0:3], v[188:191], v[228:231], v[0:3]
	s_waitcnt vmcnt(6)
	s_setprio 0
	s_barrier
	s_add_i32 s66, s66, 2
	s_add_u32 s44, s44, 0x100
	s_addc_u32 s45, s45, 0
	s_add_u32 s64, s64, 0x100
	s_addc_u32 s65, s65, 0
	s_cmp_gt_u32 s66, 13
	s_cbranch_scc0 .Lffn_kA
	s_branch .Lffn_kdone
.Lffn_kB:
	s_add_u32 s46, s44, 0xfffc0080
	s_addc_u32 s47, s45, -1
	s_add_u32 s70, s44, 0x100
	s_addc_u32 s71, s45, 0
	s_add_u32 s72, s62, 0x40080
	s_addc_u32 s73, s17, 0
	s_cmp_eq_u32 s66, 12
	s_cselect_b32 s49, s17, s47
	s_cselect_b32 s48, s62, s46
	s_cselect_b32 s47, s15, s65
	s_cselect_b32 s46, s63, s64
	s_cselect_b32 s70, s72, s70
	s_cselect_b32 s71, s73, s71
	s_add_u32 s68, s46, 0x40000
	s_addc_u32 s69, s47, 0
	s_add_u32 s100, s48, 0x40000
	s_addc_u32 s101, s49, 0
	v_add_u32_e32 v145, 0x10000, v143
	ds_read_b128 v[146:149], v145
	ds_read_b128 v[150:153], v145 offset:1024
	ds_read_b128 v[154:157], v145 offset:2048
	ds_read_b128 v[158:161], v145 offset:3072
	v_add_u32_e32 v145, 0x14000, v143
	ds_read_b128 v[176:179], v145
	ds_read_b128 v[180:183], v145 offset:1024
	ds_read_b128 v[184:187], v145 offset:2048
	ds_read_b128 v[188:191], v145 offset:3072
	ds_read_b128 v[192:195], v144
	ds_read_b128 v[196:199], v144 offset:1024
	ds_read_b128 v[208:211], v144 offset:2048
	ds_read_b128 v[212:215], v144 offset:3072
	ds_read_b128 v[216:219], v144 offset:4096
	ds_read_b128 v[220:223], v144 offset:5120
	ds_read_b128 v[224:227], v144 offset:6144
	ds_read_b128 v[228:231], v144 offset:7168
	ds_read_b128 v[232:235], v144 offset:16384
	ds_read_b128 v[236:239], v144 offset:17408
	ds_read_b128 v[240:243], v144 offset:18432
	ds_read_b128 v[244:247], v144 offset:19456
	s_waitcnt vmcnt(2)
	s_waitcnt lgkmcnt(0)
	s_setprio 1
	s_barrier
	v_mfma_f32_16x16x32_bf16 v[126:129], v[146:149], v[192:195], v[126:129]
	s_add_i32 m0, s39, 0x10000
	v_mfma_f32_16x16x32_bf16 v[118:121], v[154:157], v[192:195], v[118:121]
	global_load_lds_dwordx4 v134, s[46:47]
	v_mfma_f32_16x16x32_bf16 v[122:125], v[176:179], v[192:195], v[122:125]
	v_mfma_f32_16x16x32_bf16 v[114:117], v[184:187], v[192:195], v[114:117]
	s_add_i32 m0, s39, 0x12000
	v_mfma_f32_16x16x32_bf16 v[126:129], v[150:153], v[196:199], v[126:129]
	global_load_lds_dwordx4 v130, s[46:47]
	v_mfma_f32_16x16x32_bf16 v[118:121], v[158:161], v[196:199], v[118:121]
	v_mfma_f32_16x16x32_bf16 v[122:125], v[180:183], v[196:199], v[122:125]
	v_mfma_f32_16x16x32_bf16 v[114:117], v[188:191], v[196:199], v[114:117]
	ds_read_b128 v[192:195], v144 offset:20480
	ds_read_b128 v[196:199], v144 offset:21504
	v_mfma_f32_16x16x32_bf16 v[110:113], v[146:149], v[208:211], v[110:113]
	v_mfma_f32_16x16x32_bf16 v[102:105], v[154:157], v[208:211], v[102:105]
	s_add_i32 m0, s39, 0x14000
	v_mfma_f32_16x16x32_bf16 v[106:109], v[176:179], v[208:211], v[106:109]
	global_load_lds_dwordx4 v134, s[68:69]
	v_mfma_f32_16x16x32_bf16 v[98:101], v[184:187], v[208:211], v[98:101]
	v_mfma_f32_16x16x32_bf16 v[110:113], v[150:153], v[212:215], v[110:113]
	s_add_i32 m0, s39, 0x16000
	v_mfma_f32_16x16x32_bf16 v[102:105], v[158:161], v[212:215], v[102:105]
	global_load_lds_dwordx4 v130, s[68:69]
	v_mfma_f32_16x16x32_bf16 v[106:109], v[180:183], v[212:215], v[106:109]
	v_mfma_f32_16x16x32_bf16 v[98:101], v[188:191], v[212:215], v[98:101]
	ds_read_b128 v[208:211], v144 offset:22528
	ds_read_b128 v[212:215], v144 offset:23552
	s_add_i32 m0, s39, 0x0
	v_mfma_f32_16x16x32_bf16 v[94:97], v[146:149], v[216:219], v[94:97]
	global_load_lds_dwordx4 v136, s[48:49]
; #define PG8_STAGE(bufoff, gbase, voff) do { _Pragma("unroll") for (int _i = 0; _i < 2; ++_i) \
;         __builtin_amdgcn_global_load_lds((const unsigned*)((const char*)(gbase) + (voff)[_i]), (PG8_LAS unsigned*)(lds + (bufoff) + ldsw + _i * 8192), 16, 0, 0); } while (0)
; #define PG8_LDA(dst, b, h) do { _Pragma("unroll") for (int m = 0; m < 4; ++m) _Pragma("unroll") for (int k = 0; k < 2; ++k) dst[m][k] = *(const PG8_LAS bf16x8*)(lds + PG8_SA(b, h) + aoff + m * 2048 + k * 1024); } while (0)
; #define PG8_LDB(dst, b, h) do { _Pragma("unroll") for (int n = 0; n < 2; ++n) _Pragma("unroll") for (int k = 0; k < 2; ++k) dst[n][k] = *(const PG8_LAS bf16x8*)(lds + PG8_SB(b, h) + boff + n * 2048 + k * 1024); } while (0)
; #define PG8_MMA(ai, bj, At, Bt) do { __builtin_amdgcn_s_setprio(1); _Pragma("unroll") for (int m = 0; m < 4; ++m) _Pragma("unroll") for (int n = 0; n < 2; ++n) _Pragma("unroll") for (int k = 0; k < 2; ++k) \
;         acc[ai][bj][m][n] = __builtin_amdgcn_mfma_f32_16x16x32_bf16(Bt[n][k], At[m][k], acc[ai][bj][m][n], 0, 0, 0); __builtin_amdgcn_s_setprio(0); } while (0)
; #define PG8_WAIT_V(n) asm volatile("s_waitcnt vmcnt(" #n ")" ::: "memory")
; #define PG8_WAIT_L(n) asm volatile("s_waitcnt lgkmcnt(" #n ")" ::: "memory")
; #define PG8_BAR __builtin_amdgcn_s_barrier()
; #define PG8_SCHED __builtin_amdgcn_sched_barrier(0)
; template <class Epi, class Sched, bool ALIGN_EPI = false, bool SP2 = false>
; __device__ __forceinline__ void gemm_phase(PG8_LAS unsigned char* lds, const Gemm g, const Sched& S, const Epi& E) {
;     ...
;             PG8_WAIT_V(8); PG8_WAIT_L(0); PG8_BAR; PG8_MMA(0, 0, At, B0); PG8_MMA(0, 1, At, B1); PG8_BAR; PG8_SCHED;
;             PG8_LDA(At, 0, 1); PG8_STAGE(PG8_SB(0, 0), b2, voffB); PG8_STAGE(PG8_SB(0, 1), b2 + hstep, voffB); PG8_STAGE(PG8_SA(0, 0), a2, voffA);
;             PG8_WAIT_V(8); PG8_WAIT_L(0); PG8_BAR; PG8_MMA(1, 0, At, B0); PG8_MMA(1, 1, At, B1); PG8_BAR; PG8_SCHED;
;             PG8_LDB(B0, 1, 0); PG8_LDB(B1, 1, 1); PG8_SCHED; PG8_LDA(At, 1, 0); PG8_STAGE(PG8_SA(0, 1), a2 + hstep, voffA);
;             PG8_WAIT_V(8); PG8_WAIT_L(0); PG8_BAR; PG8_MMA(0, 0, At, B0); PG8_MMA(0, 1, At, B1); PG8_BAR; PG8_SCHED;
	v_mfma_f32_16x16x32_bf16 v[86:89], v[154:157], v[216:219], v[86:89]
	v_mfma_f32_16x16x32_bf16 v[90:93], v[176:179], v[216:219], v[90:93]
	s_add_i32 m0, s39, 0x2000
	v_mfma_f32_16x16x32_bf16 v[82:85], v[184:187], v[216:219], v[82:85]
	global_load_lds_dwordx4 v132, s[48:49]
	v_mfma_f32_16x16x32_bf16 v[94:97], v[150:153], v[220:223], v[94:97]
	v_mfma_f32_16x16x32_bf16 v[86:89], v[158:161], v[220:223], v[86:89]
	v_mfma_f32_16x16x32_bf16 v[90:93], v[180:183], v[220:223], v[90:93]
	v_mfma_f32_16x16x32_bf16 v[82:85], v[188:191], v[220:223], v[82:85]
	v_mfma_f32_16x16x32_bf16 v[76:79], v[146:149], v[224:227], v[76:79]
	v_mfma_f32_16x16x32_bf16 v[68:71], v[154:157], v[224:227], v[68:71]
	v_mfma_f32_16x16x32_bf16 v[72:75], v[176:179], v[224:227], v[72:75]
	v_mfma_f32_16x16x32_bf16 v[64:67], v[184:187], v[224:227], v[64:67]
	v_mfma_f32_16x16x32_bf16 v[76:79], v[150:153], v[228:231], v[76:79]
	v_mfma_f32_16x16x32_bf16 v[68:71], v[158:161], v[228:231], v[68:71]
	v_mfma_f32_16x16x32_bf16 v[72:75], v[180:183], v[228:231], v[72:75]
	v_mfma_f32_16x16x32_bf16 v[64:67], v[188:191], v[228:231], v[64:67]
	v_mfma_f32_16x16x32_bf16 v[60:63], v[146:149], v[232:235], v[60:63]
	v_mfma_f32_16x16x32_bf16 v[52:55], v[154:157], v[232:235], v[52:55]
	v_mfma_f32_16x16x32_bf16 v[56:59], v[176:179], v[232:235], v[56:59]
	v_mfma_f32_16x16x32_bf16 v[48:51], v[184:187], v[232:235], v[48:51]
	v_mfma_f32_16x16x32_bf16 v[60:63], v[150:153], v[236:239], v[60:63]
	v_mfma_f32_16x16x32_bf16 v[52:55], v[158:161], v[236:239], v[52:55]
	v_mfma_f32_16x16x32_bf16 v[56:59], v[180:183], v[236:239], v[56:59]
	v_mfma_f32_16x16x32_bf16 v[48:51], v[188:191], v[236:239], v[48:51]
	v_mfma_f32_16x16x32_bf16 v[44:47], v[146:149], v[240:243], v[44:47]
	v_mfma_f32_16x16x32_bf16 v[36:39], v[154:157], v[240:243], v[36:39]
	v_mfma_f32_16x16x32_bf16 v[40:43], v[176:179], v[240:243], v[40:43]
	v_mfma_f32_16x16x32_bf16 v[32:35], v[184:187], v[240:243], v[32:35]
	v_mfma_f32_16x16x32_bf16 v[44:47], v[150:153], v[244:247], v[44:47]
	v_mfma_f32_16x16x32_bf16 v[36:39], v[158:161], v[244:247], v[36:39]
	v_mfma_f32_16x16x32_bf16 v[40:43], v[180:183], v[244:247], v[40:43]
	v_mfma_f32_16x16x32_bf16 v[32:35], v[188:191], v[244:247], v[32:35]
	s_waitcnt lgkmcnt(2)
	v_mfma_f32_16x16x32_bf16 v[28:31], v[146:149], v[192:195], v[28:31]
	v_mfma_f32_16x16x32_bf16 v[20:23], v[154:157], v[192:195], v[20:23]
	v_mfma_f32_16x16x32_bf16 v[24:27], v[176:179], v[192:195], v[24:27]
	v_mfma_f32_16x16x32_bf16 v[16:19], v[184:187], v[192:195], v[16:19]
	v_mfma_f32_16x16x32_bf16 v[28:31], v[150:153], v[196:199], v[28:31]
	v_mfma_f32_16x16x32_bf16 v[20:23], v[158:161], v[196:199], v[20:23]
	v_mfma_f32_16x16x32_bf16 v[24:27], v[180:183], v[196:199], v[24:27]
	v_mfma_f32_16x16x32_bf16 v[16:19], v[188:191], v[196:199], v[16:19]
	s_waitcnt lgkmcnt(0)
	v_mfma_f32_16x16x32_bf16 v[12:15], v[146:149], v[208:211], v[12:15]
	v_mfma_f32_16x16x32_bf16 v[4:7], v[154:157], v[208:211], v[4:7]
	v_mfma_f32_16x16x32_bf16 v[8:11], v[176:179], v[208:211], v[8:11]
	v_mfma_f32_16x16x32_bf16 v[0:3], v[184:187], v[208:211], v[0:3]
	v_mfma_f32_16x16x32_bf16 v[12:15], v[150:153], v[212:215], v[12:15]
	v_mfma_f32_16x16x32_bf16 v[4:7], v[158:161], v[212:215], v[4:7]
	v_mfma_f32_16x16x32_bf16 v[8:11], v[180:183], v[212:215], v[8:11]
	v_mfma_f32_16x16x32_bf16 v[0:3], v[188:191], v[212:215], v[0:3]
	s_setprio 0
	s_barrier
	s_add_i32 m0, s39, 0x4000
	s_nop 0
	global_load_lds_dwordx4 v136, s[100:101]
	s_add_i32 m0, s39, 0x6000
	s_nop 0
	global_load_lds_dwordx4 v132, s[100:101]
	s_add_u32 s46, s46, 0x80
	s_addc_u32 s47, s47, 0
	s_add_u32 s68, s68, 0x80
	s_addc_u32 s69, s69, 0
	s_add_u32 s48, s48, 0x80
	s_addc_u32 s49, s49, 0
	v_add_u32_e32 v145, 0x18000, v143
	ds_read_b128 v[146:149], v145
	ds_read_b128 v[150:153], v145 offset:1024
	ds_read_b128 v[154:157], v145 offset:2048
	ds_read_b128 v[158:161], v145 offset:3072
	v_add_u32_e32 v145, 0x1c000, v143
	ds_read_b128 v[176:179], v145
	ds_read_b128 v[180:183], v145 offset:1024
	ds_read_b128 v[184:187], v145 offset:2048
	ds_read_b128 v[188:191], v145 offset:3072
	ds_read_b128 v[192:195], v144 offset:32768
	ds_read_b128 v[196:199], v144 offset:33792
	ds_read_b128 v[208:211], v144 offset:34816
	ds_read_b128 v[212:215], v144 offset:35840
	ds_read_b128 v[216:219], v144 offset:36864
	ds_read_b128 v[220:223], v144 offset:37888
	ds_read_b128 v[224:227], v144 offset:38912
	ds_read_b128 v[228:231], v144 offset:39936
	s_waitcnt vmcnt(8)
	s_waitcnt lgkmcnt(0)
	s_setprio 1
	s_barrier
; #define PG8_STAGE(bufoff, gbase, voff) do { _Pragma("unroll") for (int _i = 0; _i < 2; ++_i) \
;         __builtin_amdgcn_global_load_lds((const unsigned*)((const char*)(gbase) + (voff)[_i]), (PG8_LAS unsigned*)(lds + (bufoff) + ldsw + _i * 8192), 16, 0, 0); } while (0)
; #define PG8_LDA(dst, b, h) do { _Pragma("unroll") for (int m = 0; m < 4; ++m) _Pragma("unroll") for (int k = 0; k < 2; ++k) dst[m][k] = *(const PG8_LAS bf16x8*)(lds + PG8_SA(b, h) + aoff + m * 2048 + k * 1024); } while (0)
; #define PG8_LDB(dst, b, h) do { _Pragma("unroll") for (int n = 0; n < 2; ++n) _Pragma("unroll") for (int k = 0; k < 2; ++k) dst[n][k] = *(const PG8_LAS bf16x8*)(lds + PG8_SB(b, h) + boff + n * 2048 + k * 1024); } while (0)
; #define PG8_MMA(ai, bj, At, Bt) do { __builtin_amdgcn_s_setprio(1); _Pragma("unroll") for (int m = 0; m < 4; ++m) _Pragma("unroll") for (int n = 0; n < 2; ++n) _Pragma("unroll") for (int k = 0; k < 2; ++k) \
;         acc[ai][bj][m][n] = __builtin_amdgcn_mfma_f32_16x16x32_bf16(Bt[n][k], At[m][k], acc[ai][bj][m][n], 0, 0, 0); __builtin_amdgcn_s_setprio(0); } while (0)
; #define PG8_WAIT_V(n) asm volatile("s_waitcnt vmcnt(" #n ")" ::: "memory")
; #define PG8_WAIT_L(n) asm volatile("s_waitcnt lgkmcnt(" #n ")" ::: "memory")
; #define PG8_BAR __builtin_amdgcn_s_barrier()
; #define PG8_SCHED __builtin_amdgcn_sched_barrier(0)
; template <class Epi, class Sched, bool ALIGN_EPI = false, bool SP2 = false>
; __device__ __forceinline__ void gemm_phase(PG8_LAS unsigned char* lds, const Gemm g, const Sched& S, const Epi& E) {
;     ...
;             PG8_LDB(B0, 1, 0); PG8_LDB(B1, 1, 1); PG8_SCHED; PG8_LDA(At, 1, 0); PG8_STAGE(PG8_SA(0, 1), a2 + hstep, voffA);
;             PG8_WAIT_V(8); PG8_WAIT_L(0); PG8_BAR; PG8_MMA(0, 0, At, B0); PG8_MMA(0, 1, At, B1); PG8_BAR; PG8_SCHED;
;             PG8_LDA(At, 1, 1); PG8_STAGE(PG8_SB(1, 0), b3, voffB); PG8_STAGE(PG8_SB(1, 1), b3 + hstep, voffB); PG8_STAGE(PG8_SA(1, 0), a3, voffA);
;             PG8_WAIT_V(8); PG8_WAIT_L(0); PG8_BAR; PG8_MMA(1, 0, At, B0); PG8_MMA(1, 1, At, B1); PG8_BAR; PG8_SCHED;
	v_mfma_f32_16x16x32_bf16 v[126:129], v[146:149], v[192:195], v[126:129]
	s_add_i32 m0, s39, 0x18000
	v_mfma_f32_16x16x32_bf16 v[118:121], v[154:157], v[192:195], v[118:121]
	global_load_lds_dwordx4 v134, s[46:47]
	v_mfma_f32_16x16x32_bf16 v[122:125], v[176:179], v[192:195], v[122:125]
	v_mfma_f32_16x16x32_bf16 v[114:117], v[184:187], v[192:195], v[114:117]
	s_add_i32 m0, s39, 0x1a000
	v_mfma_f32_16x16x32_bf16 v[126:129], v[150:153], v[196:199], v[126:129]
	global_load_lds_dwordx4 v130, s[46:47]
	v_mfma_f32_16x16x32_bf16 v[118:121], v[158:161], v[196:199], v[118:121]
	v_mfma_f32_16x16x32_bf16 v[122:125], v[180:183], v[196:199], v[122:125]
	s_add_i32 m0, s39, 0x1c000
	v_mfma_f32_16x16x32_bf16 v[114:117], v[188:191], v[196:199], v[114:117]
	global_load_lds_dwordx4 v134, s[68:69]
	v_mfma_f32_16x16x32_bf16 v[110:113], v[146:149], v[208:211], v[110:113]
	v_mfma_f32_16x16x32_bf16 v[102:105], v[154:157], v[208:211], v[102:105]
	s_add_i32 m0, s39, 0x1e000
	v_mfma_f32_16x16x32_bf16 v[106:109], v[176:179], v[208:211], v[106:109]
	global_load_lds_dwordx4 v130, s[68:69]
	v_mfma_f32_16x16x32_bf16 v[98:101], v[184:187], v[208:211], v[98:101]
	v_mfma_f32_16x16x32_bf16 v[110:113], v[150:153], v[212:215], v[110:113]
	s_add_i32 m0, s39, 0x8000
	v_mfma_f32_16x16x32_bf16 v[102:105], v[158:161], v[212:215], v[102:105]
	global_load_lds_dwordx4 v136, s[48:49]
	v_mfma_f32_16x16x32_bf16 v[106:109], v[180:183], v[212:215], v[106:109]
	v_mfma_f32_16x16x32_bf16 v[98:101], v[188:191], v[212:215], v[98:101]
	s_add_i32 m0, s39, 0xa000
	v_mfma_f32_16x16x32_bf16 v[94:97], v[146:149], v[216:219], v[94:97]
	global_load_lds_dwordx4 v132, s[48:49]
	v_mfma_f32_16x16x32_bf16 v[86:89], v[154:157], v[216:219], v[86:89]
	v_mfma_f32_16x16x32_bf16 v[90:93], v[176:179], v[216:219], v[90:93]
	v_mfma_f32_16x16x32_bf16 v[82:85], v[184:187], v[216:219], v[82:85]
	v_mfma_f32_16x16x32_bf16 v[94:97], v[150:153], v[220:223], v[94:97]
	v_mfma_f32_16x16x32_bf16 v[86:89], v[158:161], v[220:223], v[86:89]
	v_mfma_f32_16x16x32_bf16 v[90:93], v[180:183], v[220:223], v[90:93]
	v_mfma_f32_16x16x32_bf16 v[82:85], v[188:191], v[220:223], v[82:85]
	v_mfma_f32_16x16x32_bf16 v[76:79], v[146:149], v[224:227], v[76:79]
	v_mfma_f32_16x16x32_bf16 v[68:71], v[154:157], v[224:227], v[68:71]
	v_mfma_f32_16x16x32_bf16 v[72:75], v[176:179], v[224:227], v[72:75]
	v_mfma_f32_16x16x32_bf16 v[64:67], v[184:187], v[224:227], v[64:67]
	v_mfma_f32_16x16x32_bf16 v[76:79], v[150:153], v[228:231], v[76:79]
	v_mfma_f32_16x16x32_bf16 v[68:71], v[158:161], v[228:231], v[68:71]
	v_mfma_f32_16x16x32_bf16 v[72:75], v[180:183], v[228:231], v[72:75]
	v_mfma_f32_16x16x32_bf16 v[64:67], v[188:191], v[228:231], v[64:67]
	s_setprio 0
	s_barrier
	ds_read_b128 v[192:195], v144 offset:49152
	ds_read_b128 v[196:199], v144 offset:50176
	ds_read_b128 v[208:211], v144 offset:51200
	ds_read_b128 v[212:215], v144 offset:52224
	ds_read_b128 v[216:219], v144 offset:53248
	ds_read_b128 v[220:223], v144 offset:54272
	ds_read_b128 v[224:227], v144 offset:55296
	ds_read_b128 v[228:231], v144 offset:56320
	s_waitcnt vmcnt(8)
	s_waitcnt lgkmcnt(0)
	s_setprio 1
	s_barrier
	v_mfma_f32_16x16x32_bf16 v[60:63], v[146:149], v[192:195], v[60:63]
	s_add_i32 m0, s39, 0xc000
	v_mfma_f32_16x16x32_bf16 v[52:55], v[154:157], v[192:195], v[52:55]
	global_load_lds_dwordx4 v138, s[70:71]
	v_mfma_f32_16x16x32_bf16 v[56:59], v[176:179], v[192:195], v[56:59]
	v_mfma_f32_16x16x32_bf16 v[48:51], v[184:187], v[192:195], v[48:51]
	s_add_i32 m0, s39, 0xe000
	v_mfma_f32_16x16x32_bf16 v[60:63], v[150:153], v[196:199], v[60:63]
	global_load_lds_dwordx4 v140, s[70:71]
	v_mfma_f32_16x16x32_bf16 v[52:55], v[158:161], v[196:199], v[52:55]
	v_mfma_f32_16x16x32_bf16 v[56:59], v[180:183], v[196:199], v[56:59]
	v_mfma_f32_16x16x32_bf16 v[48:51], v[188:191], v[196:199], v[48:51]
	v_mfma_f32_16x16x32_bf16 v[44:47], v[146:149], v[208:211], v[44:47]
	v_mfma_f32_16x16x32_bf16 v[36:39], v[154:157], v[208:211], v[36:39]
	v_mfma_f32_16x16x32_bf16 v[40:43], v[176:179], v[208:211], v[40:43]
	v_mfma_f32_16x16x32_bf16 v[32:35], v[184:187], v[208:211], v[32:35]
	v_mfma_f32_16x16x32_bf16 v[44:47], v[150:153], v[212:215], v[44:47]
	v_mfma_f32_16x16x32_bf16 v[36:39], v[158:161], v[212:215], v[36:39]
	v_mfma_f32_16x16x32_bf16 v[40:43], v[180:183], v[212:215], v[40:43]
	v_mfma_f32_16x16x32_bf16 v[32:35], v[188:191], v[212:215], v[32:35]
	v_mfma_f32_16x16x32_bf16 v[28:31], v[146:149], v[216:219], v[28:31]
	v_mfma_f32_16x16x32_bf16 v[20:23], v[154:157], v[216:219], v[20:23]
	v_mfma_f32_16x16x32_bf16 v[24:27], v[176:179], v[216:219], v[24:27]
	v_mfma_f32_16x16x32_bf16 v[16:19], v[184:187], v[216:219], v[16:19]
	v_mfma_f32_16x16x32_bf16 v[28:31], v[150:153], v[220:223], v[28:31]
	v_mfma_f32_16x16x32_bf16 v[20:23], v[158:161], v[220:223], v[20:23]
	v_mfma_f32_16x16x32_bf16 v[24:27], v[180:183], v[220:223], v[24:27]
	v_mfma_f32_16x16x32_bf16 v[16:19], v[188:191], v[220:223], v[16:19]
	v_mfma_f32_16x16x32_bf16 v[12:15], v[146:149], v[224:227], v[12:15]
	v_mfma_f32_16x16x32_bf16 v[4:7], v[154:157], v[224:227], v[4:7]
	v_mfma_f32_16x16x32_bf16 v[8:11], v[176:179], v[224:227], v[8:11]
	v_mfma_f32_16x16x32_bf16 v[0:3], v[184:187], v[224:227], v[0:3]
	v_mfma_f32_16x16x32_bf16 v[12:15], v[150:153], v[228:231], v[12:15]
	v_mfma_f32_16x16x32_bf16 v[4:7], v[158:161], v[228:231], v[4:7]
	v_mfma_f32_16x16x32_bf16 v[8:11], v[180:183], v[228:231], v[8:11]
	v_mfma_f32_16x16x32_bf16 v[0:3], v[188:191], v[228:231], v[0:3]
	s_waitcnt vmcnt(8)
	s_setprio 0
	s_barrier
	s_add_i32 s66, s66, 2
	s_add_u32 s44, s44, 0x100
	s_addc_u32 s45, s45, 0
	s_add_u32 s64, s64, 0x100
	s_addc_u32 s65, s65, 0
	s_cmp_gt_u32 s66, 13
	s_cbranch_scc0 .Lffn_kB
